# residual-stream f32 X loads/stores in the out-proj/down epilogues use the nt (streaming) cache policy; bf16 copy keeps the default policy
# baseline (speedup 1.0000x reference)
.LBB0_522:
	s_load_dwordx2 s[48:49], s[46:47], 0x18
	v_lshl_add_u32 v170, s53, 8, v149
	v_lshl_or_b32 v168, s52, 8, v173
	v_lshlrev_b32_e32 v199, 11, v170
	v_add_lshl_u32 v199, v199, v168, 2
	v_lshlrev_b32_e32 v200, 2, v168
	v_lshlrev_b32_e32 v201, 7, v170
	s_waitcnt lgkmcnt(0)
	s_add_u32 s46, s50, 0xdf00000
	s_addc_u32 s47, s51, 0
	s_add_u32 s48, s48, s37
	s_addc_u32 s49, s49, 0
	s_add_u32 s98, s50, 0x9f00000
	s_addc_u32 s99, s51, 0
	s_lshl_b32 s52, s52, 2
	s_ashr_i32 s53, s52, 31
	s_lshl_b64 s[52:53], s[52:53], 2
	s_add_u32 s13, s50, s52
	s_addc_u32 s21, s51, s53
	s_add_u32 s13, s13, s54
	s_addc_u32 s21, s21, 0
	s_add_u32 s50, s13, 0x1a700000
	s_addc_u32 s51, s21, 0
	global_load_dwordx4 v[102:105], v200, s[48:49] nt
	global_load_dwordx4 v[98:101], v200, s[48:49] offset:16 nt
	global_load_dwordx4 v[86:89], v200, s[48:49] offset:512 nt
	global_load_dwordx4 v[82:85], v200, s[48:49] offset:528 nt
	v_mov_b32_e32 v154, v199
	global_load_dwordx4 v[210:213], v154, s[44:45] nt
	global_load_dwordx4 v[214:217], v154, s[44:45] offset:16 nt
	global_load_dwordx4 v[218:221], v154, s[44:45] offset:512 nt
	global_load_dwordx4 v[222:225], v154, s[44:45] offset:528 nt
	v_add_u32_e32 v155, 0x20000, v199
	global_load_dwordx4 v[226:229], v155, s[44:45] nt
	global_load_dwordx4 v[236:239], v155, s[44:45] offset:16 nt
	global_load_dwordx4 v[240:243], v155, s[44:45] offset:512 nt
	global_load_dwordx4 v[244:247], v155, s[44:45] offset:528 nt
	v_add_u32_e32 v156, 0x40000, v199
	global_load_dwordx4 v[180:183], v156, s[44:45] nt
	global_load_dwordx4 v[184:187], v156, s[44:45] offset:16 nt
	s_waitcnt vmcnt(8)
	v_pk_add_f32 v[142:143], v[142:143], v[210:211]
	v_pk_add_f32 v[144:145], v[144:145], v[212:213]
	v_pk_add_f32 v[138:139], v[138:139], v[214:215]
	v_pk_add_f32 v[140:141], v[140:141], v[216:217]
	global_store_dwordx4 v154, v[142:145], s[98:99] nt
	global_store_dwordx4 v154, v[138:141], s[98:99] offset:16 nt
	v_pk_mul_f32 v[210:211], v[102:103], v[142:143]
	v_pk_mul_f32 v[212:213], v[104:105], v[144:145]
	v_pk_mul_f32 v[214:215], v[98:99], v[138:139]
	v_pk_mul_f32 v[216:217], v[100:101], v[140:141]
	v_cvt_pk_bf16_f32 v188, v210, v211
	v_cvt_pk_bf16_f32 v189, v212, v213
	v_cvt_pk_bf16_f32 v190, v214, v215
	v_cvt_pk_bf16_f32 v191, v216, v217
	v_lshrrev_b32_e32 v202, 1, v154
	global_store_dwordx4 v202, v[188:191], s[46:47]
	v_mul_f32_e32 v196, v142, v142
	v_fmac_f32_e32 v196, v143, v143
	v_fmac_f32_e32 v196, v144, v144
	v_fmac_f32_e32 v196, v145, v145
	v_fmac_f32_e32 v196, v138, v138
	v_fmac_f32_e32 v196, v139, v139
	v_fmac_f32_e32 v196, v140, v140
	v_fmac_f32_e32 v196, v141, v141
	global_load_dwordx4 v[210:213], v156, s[44:45] offset:512 nt
	global_load_dwordx4 v[214:217], v156, s[44:45] offset:528 nt
	s_waitcnt vmcnt(11)
	v_pk_add_f32 v[134:135], v[134:135], v[218:219]
	v_pk_add_f32 v[136:137], v[136:137], v[220:221]
	v_pk_add_f32 v[130:131], v[130:131], v[222:223]
	v_pk_add_f32 v[132:133], v[132:133], v[224:225]
	global_store_dwordx4 v154, v[134:137], s[98:99] offset:512 nt
	global_store_dwordx4 v154, v[130:133], s[98:99] offset:528 nt
	v_pk_mul_f32 v[218:219], v[86:87], v[134:135]
	v_pk_mul_f32 v[220:221], v[88:89], v[136:137]
	v_pk_mul_f32 v[222:223], v[82:83], v[130:131]
	v_pk_mul_f32 v[224:225], v[84:85], v[132:133]
	v_cvt_pk_bf16_f32 v192, v218, v219
	v_cvt_pk_bf16_f32 v193, v220, v221
	v_cvt_pk_bf16_f32 v194, v222, v223
	v_cvt_pk_bf16_f32 v195, v224, v225
	global_store_dwordx4 v202, v[192:195], s[46:47] offset:256
	v_fmac_f32_e32 v196, v134, v134
	v_fmac_f32_e32 v196, v135, v135
	v_fmac_f32_e32 v196, v136, v136
	v_fmac_f32_e32 v196, v137, v137
	v_fmac_f32_e32 v196, v130, v130
	v_fmac_f32_e32 v196, v131, v131
	v_fmac_f32_e32 v196, v132, v132
	v_fmac_f32_e32 v196, v133, v133
	v_mov_b32_e32 v198, v196
	s_nop 1
	v_permlane16_swap_b32_e32 v196, v198
	v_add_f32_e32 v196, v196, v198
	v_mov_b32_e32 v198, v196
	s_nop 1
	v_permlane32_swap_b32_e32 v196, v198
	v_add_f32_e32 v196, v196, v198
	v_mov_b32_e32 v200, v201
	s_mov_b64 exec, s[38:39]
	global_store_dword v200, v196, s[50:51]
	s_mov_b64 exec, -1
	v_add_u32_e32 v157, 0x60000, v199
	global_load_dwordx4 v[218:221], v157, s[44:45] nt
	global_load_dwordx4 v[222:225], v157, s[44:45] offset:16 nt
	s_waitcnt vmcnt(15)
	v_pk_add_f32 v[126:127], v[126:127], v[226:227]
	v_pk_add_f32 v[128:129], v[128:129], v[228:229]
	v_pk_add_f32 v[122:123], v[122:123], v[236:237]
	v_pk_add_f32 v[124:125], v[124:125], v[238:239]
	global_store_dwordx4 v155, v[126:129], s[98:99] nt
	global_store_dwordx4 v155, v[122:125], s[98:99] offset:16 nt
	v_pk_mul_f32 v[226:227], v[102:103], v[126:127]
	v_pk_mul_f32 v[228:229], v[104:105], v[128:129]
	v_pk_mul_f32 v[236:237], v[98:99], v[122:123]
	v_pk_mul_f32 v[238:239], v[100:101], v[124:125]
	v_cvt_pk_bf16_f32 v188, v226, v227
	v_cvt_pk_bf16_f32 v189, v228, v229
	v_cvt_pk_bf16_f32 v190, v236, v237
	v_cvt_pk_bf16_f32 v191, v238, v239
	v_lshrrev_b32_e32 v203, 1, v155
	global_store_dwordx4 v203, v[188:191], s[46:47]
	v_mul_f32_e32 v197, v126, v126
	v_fmac_f32_e32 v197, v127, v127
	v_fmac_f32_e32 v197, v128, v128
	v_fmac_f32_e32 v197, v129, v129
	v_fmac_f32_e32 v197, v122, v122
	v_fmac_f32_e32 v197, v123, v123
	v_fmac_f32_e32 v197, v124, v124
	v_fmac_f32_e32 v197, v125, v125
	global_load_dwordx4 v[226:229], v157, s[44:45] offset:512 nt
	global_load_dwordx4 v[236:239], v157, s[44:45] offset:528 nt
	s_waitcnt vmcnt(18)
	v_pk_add_f32 v[118:119], v[118:119], v[240:241]
	v_pk_add_f32 v[120:121], v[120:121], v[242:243]
	v_pk_add_f32 v[114:115], v[114:115], v[244:245]
	v_pk_add_f32 v[116:117], v[116:117], v[246:247]
	global_store_dwordx4 v155, v[118:121], s[98:99] offset:512 nt
	global_store_dwordx4 v155, v[114:117], s[98:99] offset:528 nt
	v_pk_mul_f32 v[240:241], v[86:87], v[118:119]
	v_pk_mul_f32 v[242:243], v[88:89], v[120:121]
	v_pk_mul_f32 v[244:245], v[82:83], v[114:115]
	v_pk_mul_f32 v[246:247], v[84:85], v[116:117]
	v_cvt_pk_bf16_f32 v192, v240, v241
	v_cvt_pk_bf16_f32 v193, v242, v243
	v_cvt_pk_bf16_f32 v194, v244, v245
	v_cvt_pk_bf16_f32 v195, v246, v247
	global_store_dwordx4 v203, v[192:195], s[46:47] offset:256
	v_fmac_f32_e32 v197, v118, v118
	v_fmac_f32_e32 v197, v119, v119
	v_fmac_f32_e32 v197, v120, v120
	v_fmac_f32_e32 v197, v121, v121
	v_fmac_f32_e32 v197, v114, v114
	v_fmac_f32_e32 v197, v115, v115
	v_fmac_f32_e32 v197, v116, v116
	v_fmac_f32_e32 v197, v117, v117
	v_mov_b32_e32 v198, v197
	s_nop 1
	v_permlane16_swap_b32_e32 v197, v198
	v_add_f32_e32 v197, v197, v198
	v_mov_b32_e32 v198, v197
	s_nop 1
	v_permlane32_swap_b32_e32 v197, v198
	v_add_f32_e32 v197, v197, v198
	v_add_u32_e32 v200, 0x800, v201
	s_mov_b64 exec, s[38:39]
	global_store_dword v200, v197, s[50:51]
	s_mov_b64 exec, -1
	v_add_u32_e32 v154, 0x100000, v199
	global_load_dwordx4 v[240:243], v154, s[44:45] nt
	global_load_dwordx4 v[244:247], v154, s[44:45] offset:16 nt
	s_waitcnt vmcnt(22)
	v_pk_add_f32 v[110:111], v[110:111], v[180:181]
	v_pk_add_f32 v[112:113], v[112:113], v[182:183]
	v_pk_add_f32 v[106:107], v[106:107], v[184:185]
	v_pk_add_f32 v[108:109], v[108:109], v[186:187]
	global_store_dwordx4 v156, v[110:113], s[98:99] nt
	global_store_dwordx4 v156, v[106:109], s[98:99] offset:16 nt
	v_pk_mul_f32 v[180:181], v[102:103], v[110:111]
	v_pk_mul_f32 v[182:183], v[104:105], v[112:113]
	v_pk_mul_f32 v[184:185], v[98:99], v[106:107]
	v_pk_mul_f32 v[186:187], v[100:101], v[108:109]
	v_cvt_pk_bf16_f32 v188, v180, v181
	v_cvt_pk_bf16_f32 v189, v182, v183
	v_cvt_pk_bf16_f32 v190, v184, v185
	v_cvt_pk_bf16_f32 v191, v186, v187
	v_lshrrev_b32_e32 v202, 1, v156
	global_store_dwordx4 v202, v[188:191], s[46:47]
	v_mul_f32_e32 v196, v110, v110
	v_fmac_f32_e32 v196, v111, v111
	v_fmac_f32_e32 v196, v112, v112
	v_fmac_f32_e32 v196, v113, v113
	v_fmac_f32_e32 v196, v106, v106
	v_fmac_f32_e32 v196, v107, v107
	v_fmac_f32_e32 v196, v108, v108
	v_fmac_f32_e32 v196, v109, v109
	global_load_dwordx4 v[180:183], v154, s[44:45] offset:512 nt
	global_load_dwordx4 v[184:187], v154, s[44:45] offset:528 nt
	s_waitcnt vmcnt(22)
	v_pk_add_f32 v[94:95], v[94:95], v[210:211]
	v_pk_add_f32 v[96:97], v[96:97], v[212:213]
	v_pk_add_f32 v[90:91], v[90:91], v[214:215]
	v_pk_add_f32 v[92:93], v[92:93], v[216:217]
	global_store_dwordx4 v156, v[94:97], s[98:99] offset:512 nt
	global_store_dwordx4 v156, v[90:93], s[98:99] offset:528 nt
	v_pk_mul_f32 v[210:211], v[86:87], v[94:95]
	v_pk_mul_f32 v[212:213], v[88:89], v[96:97]
	v_pk_mul_f32 v[214:215], v[82:83], v[90:91]
	v_pk_mul_f32 v[216:217], v[84:85], v[92:93]
	v_cvt_pk_bf16_f32 v192, v210, v211
	v_cvt_pk_bf16_f32 v193, v212, v213
	v_cvt_pk_bf16_f32 v194, v214, v215
	v_cvt_pk_bf16_f32 v195, v216, v217
	global_store_dwordx4 v202, v[192:195], s[46:47] offset:256
	v_fmac_f32_e32 v196, v94, v94
	v_fmac_f32_e32 v196, v95, v95
	v_fmac_f32_e32 v196, v96, v96
	v_fmac_f32_e32 v196, v97, v97
	v_fmac_f32_e32 v196, v90, v90
	v_fmac_f32_e32 v196, v91, v91
	v_fmac_f32_e32 v196, v92, v92
	v_fmac_f32_e32 v196, v93, v93
	v_mov_b32_e32 v198, v196
	s_nop 1
	v_permlane16_swap_b32_e32 v196, v198
	v_add_f32_e32 v196, v196, v198
	v_mov_b32_e32 v198, v196
	s_nop 1
	v_permlane32_swap_b32_e32 v196, v198
	v_add_f32_e32 v196, v196, v198
	v_add_u32_e32 v200, 0x1000, v201
	s_mov_b64 exec, s[38:39]
	global_store_dword v200, v196, s[50:51]
	s_mov_b64 exec, -1
	v_add_u32_e32 v155, 0x120000, v199
	global_load_dwordx4 v[210:213], v155, s[44:45] nt
	global_load_dwordx4 v[214:217], v155, s[44:45] offset:16 nt
	s_waitcnt vmcnt(22)
	v_pk_add_f32 v[78:79], v[78:79], v[218:219]
	v_pk_add_f32 v[80:81], v[80:81], v[220:221]
	v_pk_add_f32 v[74:75], v[74:75], v[222:223]
	v_pk_add_f32 v[76:77], v[76:77], v[224:225]
	global_store_dwordx4 v157, v[78:81], s[98:99] nt
	global_store_dwordx4 v157, v[74:77], s[98:99] offset:16 nt
	v_pk_mul_f32 v[218:219], v[102:103], v[78:79]
	v_pk_mul_f32 v[220:221], v[104:105], v[80:81]
	v_pk_mul_f32 v[222:223], v[98:99], v[74:75]
	v_pk_mul_f32 v[224:225], v[100:101], v[76:77]
	v_cvt_pk_bf16_f32 v188, v218, v219
	v_cvt_pk_bf16_f32 v189, v220, v221
	v_cvt_pk_bf16_f32 v190, v222, v223
	v_cvt_pk_bf16_f32 v191, v224, v225
	v_lshrrev_b32_e32 v203, 1, v157
	global_store_dwordx4 v203, v[188:191], s[46:47]
	v_mul_f32_e32 v197, v78, v78
	v_fmac_f32_e32 v197, v79, v79
	v_fmac_f32_e32 v197, v80, v80
	v_fmac_f32_e32 v197, v81, v81
	v_fmac_f32_e32 v197, v74, v74
	v_fmac_f32_e32 v197, v75, v75
	v_fmac_f32_e32 v197, v76, v76
	v_fmac_f32_e32 v197, v77, v77
	global_load_dwordx4 v[218:221], v155, s[44:45] offset:512 nt
	global_load_dwordx4 v[222:225], v155, s[44:45] offset:528 nt
	s_waitcnt vmcnt(22)
	v_pk_add_f32 v[70:71], v[70:71], v[226:227]
	v_pk_add_f32 v[72:73], v[72:73], v[228:229]
	v_pk_add_f32 v[66:67], v[66:67], v[236:237]
	v_pk_add_f32 v[68:69], v[68:69], v[238:239]
	global_store_dwordx4 v157, v[70:73], s[98:99] offset:512 nt
	global_store_dwordx4 v157, v[66:69], s[98:99] offset:528 nt
	v_pk_mul_f32 v[226:227], v[86:87], v[70:71]
	v_pk_mul_f32 v[228:229], v[88:89], v[72:73]
	v_pk_mul_f32 v[236:237], v[82:83], v[66:67]
	v_pk_mul_f32 v[238:239], v[84:85], v[68:69]
	v_cvt_pk_bf16_f32 v192, v226, v227
	v_cvt_pk_bf16_f32 v193, v228, v229
	v_cvt_pk_bf16_f32 v194, v236, v237
	v_cvt_pk_bf16_f32 v195, v238, v239
	global_store_dwordx4 v203, v[192:195], s[46:47] offset:256
	v_fmac_f32_e32 v197, v70, v70
	v_fmac_f32_e32 v197, v71, v71
	v_fmac_f32_e32 v197, v72, v72
	v_fmac_f32_e32 v197, v73, v73
	v_fmac_f32_e32 v197, v66, v66
	v_fmac_f32_e32 v197, v67, v67
	v_fmac_f32_e32 v197, v68, v68
	v_fmac_f32_e32 v197, v69, v69
	v_mov_b32_e32 v198, v197
	s_nop 1
	v_permlane16_swap_b32_e32 v197, v198
	v_add_f32_e32 v197, v197, v198
	v_mov_b32_e32 v198, v197
	s_nop 1
	v_permlane32_swap_b32_e32 v197, v198
	v_add_f32_e32 v197, v197, v198
	v_add_u32_e32 v200, 0x1800, v201
	s_mov_b64 exec, s[38:39]
	global_store_dword v200, v197, s[50:51]
	s_mov_b64 exec, -1
	v_add_u32_e32 v156, 0x140000, v199
	global_load_dwordx4 v[226:229], v156, s[44:45] nt
	global_load_dwordx4 v[236:239], v156, s[44:45] offset:16 nt
	s_waitcnt vmcnt(22)
	v_pk_add_f32 v[62:63], v[62:63], v[240:241]
	v_pk_add_f32 v[64:65], v[64:65], v[242:243]
	v_pk_add_f32 v[58:59], v[58:59], v[244:245]
	v_pk_add_f32 v[60:61], v[60:61], v[246:247]
	global_store_dwordx4 v154, v[62:65], s[98:99] nt
	global_store_dwordx4 v154, v[58:61], s[98:99] offset:16 nt
	v_pk_mul_f32 v[240:241], v[102:103], v[62:63]
	v_pk_mul_f32 v[242:243], v[104:105], v[64:65]
	v_pk_mul_f32 v[244:245], v[98:99], v[58:59]
	v_pk_mul_f32 v[246:247], v[100:101], v[60:61]
	v_cvt_pk_bf16_f32 v188, v240, v241
	v_cvt_pk_bf16_f32 v189, v242, v243
	v_cvt_pk_bf16_f32 v190, v244, v245
	v_cvt_pk_bf16_f32 v191, v246, v247
	v_lshrrev_b32_e32 v202, 1, v154
	global_store_dwordx4 v202, v[188:191], s[46:47]
	v_mul_f32_e32 v196, v62, v62
	v_fmac_f32_e32 v196, v63, v63
	v_fmac_f32_e32 v196, v64, v64
	v_fmac_f32_e32 v196, v65, v65
	v_fmac_f32_e32 v196, v58, v58
	v_fmac_f32_e32 v196, v59, v59
	v_fmac_f32_e32 v196, v60, v60
	v_fmac_f32_e32 v196, v61, v61
	global_load_dwordx4 v[240:243], v156, s[44:45] offset:512 nt
	global_load_dwordx4 v[244:247], v156, s[44:45] offset:528 nt
	s_waitcnt vmcnt(22)
	v_pk_add_f32 v[54:55], v[54:55], v[180:181]
	v_pk_add_f32 v[56:57], v[56:57], v[182:183]
	v_pk_add_f32 v[50:51], v[50:51], v[184:185]
	v_pk_add_f32 v[52:53], v[52:53], v[186:187]
	global_store_dwordx4 v154, v[54:57], s[98:99] offset:512 nt
	global_store_dwordx4 v154, v[50:53], s[98:99] offset:528 nt
	v_pk_mul_f32 v[180:181], v[86:87], v[54:55]
	v_pk_mul_f32 v[182:183], v[88:89], v[56:57]
	v_pk_mul_f32 v[184:185], v[82:83], v[50:51]
	v_pk_mul_f32 v[186:187], v[84:85], v[52:53]
	v_cvt_pk_bf16_f32 v192, v180, v181
	v_cvt_pk_bf16_f32 v193, v182, v183
	v_cvt_pk_bf16_f32 v194, v184, v185
	v_cvt_pk_bf16_f32 v195, v186, v187
	global_store_dwordx4 v202, v[192:195], s[46:47] offset:256
	v_fmac_f32_e32 v196, v54, v54
	v_fmac_f32_e32 v196, v55, v55
	v_fmac_f32_e32 v196, v56, v56
	v_fmac_f32_e32 v196, v57, v57
	v_fmac_f32_e32 v196, v50, v50
	v_fmac_f32_e32 v196, v51, v51
	v_fmac_f32_e32 v196, v52, v52
	v_fmac_f32_e32 v196, v53, v53
	v_mov_b32_e32 v198, v196
	s_nop 1
	v_permlane16_swap_b32_e32 v196, v198
	v_add_f32_e32 v196, v196, v198
	v_mov_b32_e32 v198, v196
	s_nop 1
	v_permlane32_swap_b32_e32 v196, v198
	v_add_f32_e32 v196, v196, v198
	v_add_u32_e32 v200, 0x4000, v201
	s_mov_b64 exec, s[38:39]
	global_store_dword v200, v196, s[50:51]
	s_mov_b64 exec, -1
	v_add_u32_e32 v157, 0x160000, v199
	global_load_dwordx4 v[180:183], v157, s[44:45] nt
	global_load_dwordx4 v[184:187], v157, s[44:45] offset:16 nt
	s_waitcnt vmcnt(22)
	v_pk_add_f32 v[46:47], v[46:47], v[210:211]
	v_pk_add_f32 v[48:49], v[48:49], v[212:213]
	v_pk_add_f32 v[42:43], v[42:43], v[214:215]
	v_pk_add_f32 v[44:45], v[44:45], v[216:217]
	global_store_dwordx4 v155, v[46:49], s[98:99] nt
	global_store_dwordx4 v155, v[42:45], s[98:99] offset:16 nt
	v_pk_mul_f32 v[210:211], v[102:103], v[46:47]
	v_pk_mul_f32 v[212:213], v[104:105], v[48:49]
	v_pk_mul_f32 v[214:215], v[98:99], v[42:43]
	v_pk_mul_f32 v[216:217], v[100:101], v[44:45]
	v_cvt_pk_bf16_f32 v188, v210, v211
	v_cvt_pk_bf16_f32 v189, v212, v213
	v_cvt_pk_bf16_f32 v190, v214, v215
	v_cvt_pk_bf16_f32 v191, v216, v217
	v_lshrrev_b32_e32 v203, 1, v155
	global_store_dwordx4 v203, v[188:191], s[46:47]
	v_mul_f32_e32 v197, v46, v46
	v_fmac_f32_e32 v197, v47, v47
	v_fmac_f32_e32 v197, v48, v48
	v_fmac_f32_e32 v197, v49, v49
	v_fmac_f32_e32 v197, v42, v42
	v_fmac_f32_e32 v197, v43, v43
	v_fmac_f32_e32 v197, v44, v44
	v_fmac_f32_e32 v197, v45, v45
	global_load_dwordx4 v[210:213], v157, s[44:45] offset:512 nt
	global_load_dwordx4 v[214:217], v157, s[44:45] offset:528 nt
	s_waitcnt vmcnt(22)
	v_pk_add_f32 v[38:39], v[38:39], v[218:219]
	v_pk_add_f32 v[40:41], v[40:41], v[220:221]
	v_pk_add_f32 v[34:35], v[34:35], v[222:223]
	v_pk_add_f32 v[36:37], v[36:37], v[224:225]
	global_store_dwordx4 v155, v[38:41], s[98:99] offset:512 nt
	global_store_dwordx4 v155, v[34:37], s[98:99] offset:528 nt
	v_pk_mul_f32 v[218:219], v[86:87], v[38:39]
	v_pk_mul_f32 v[220:221], v[88:89], v[40:41]
	v_pk_mul_f32 v[222:223], v[82:83], v[34:35]
	v_pk_mul_f32 v[224:225], v[84:85], v[36:37]
	v_cvt_pk_bf16_f32 v192, v218, v219
	v_cvt_pk_bf16_f32 v193, v220, v221
	v_cvt_pk_bf16_f32 v194, v222, v223
	v_cvt_pk_bf16_f32 v195, v224, v225
	global_store_dwordx4 v203, v[192:195], s[46:47] offset:256
	v_fmac_f32_e32 v197, v38, v38
	v_fmac_f32_e32 v197, v39, v39
	v_fmac_f32_e32 v197, v40, v40
	v_fmac_f32_e32 v197, v41, v41
	v_fmac_f32_e32 v197, v34, v34
	v_fmac_f32_e32 v197, v35, v35
	v_fmac_f32_e32 v197, v36, v36
	v_fmac_f32_e32 v197, v37, v37
	v_mov_b32_e32 v198, v197
	s_nop 1
	v_permlane16_swap_b32_e32 v197, v198
	v_add_f32_e32 v197, v197, v198
	v_mov_b32_e32 v198, v197
	s_nop 1
	v_permlane32_swap_b32_e32 v197, v198
	v_add_f32_e32 v197, v197, v198
	v_add_u32_e32 v200, 0x4800, v201
	s_mov_b64 exec, s[38:39]
	global_store_dword v200, v197, s[50:51]
	s_mov_b64 exec, -1
	s_waitcnt vmcnt(20)
	v_pk_add_f32 v[30:31], v[30:31], v[226:227]
	v_pk_add_f32 v[32:33], v[32:33], v[228:229]
	v_pk_add_f32 v[26:27], v[26:27], v[236:237]
	v_pk_add_f32 v[28:29], v[28:29], v[238:239]
	global_store_dwordx4 v156, v[30:33], s[98:99] nt
	global_store_dwordx4 v156, v[26:29], s[98:99] offset:16 nt
	v_pk_mul_f32 v[226:227], v[102:103], v[30:31]
	v_pk_mul_f32 v[228:229], v[104:105], v[32:33]
	v_pk_mul_f32 v[236:237], v[98:99], v[26:27]
	v_pk_mul_f32 v[238:239], v[100:101], v[28:29]
	v_cvt_pk_bf16_f32 v188, v226, v227
	v_cvt_pk_bf16_f32 v189, v228, v229
	v_cvt_pk_bf16_f32 v190, v236, v237
	v_cvt_pk_bf16_f32 v191, v238, v239
	v_lshrrev_b32_e32 v202, 1, v156
	global_store_dwordx4 v202, v[188:191], s[46:47]
	v_mul_f32_e32 v196, v30, v30
	v_fmac_f32_e32 v196, v31, v31
	v_fmac_f32_e32 v196, v32, v32
	v_fmac_f32_e32 v196, v33, v33
	v_fmac_f32_e32 v196, v26, v26
	v_fmac_f32_e32 v196, v27, v27
	v_fmac_f32_e32 v196, v28, v28
	v_fmac_f32_e32 v196, v29, v29
	s_waitcnt vmcnt(18)
	v_pk_add_f32 v[22:23], v[22:23], v[240:241]
	v_pk_add_f32 v[24:25], v[24:25], v[242:243]
	v_pk_add_f32 v[18:19], v[18:19], v[244:245]
	v_pk_add_f32 v[20:21], v[20:21], v[246:247]
	global_store_dwordx4 v156, v[22:25], s[98:99] offset:512 nt
	global_store_dwordx4 v156, v[18:21], s[98:99] offset:528 nt
	v_pk_mul_f32 v[240:241], v[86:87], v[22:23]
	v_pk_mul_f32 v[242:243], v[88:89], v[24:25]
	v_pk_mul_f32 v[244:245], v[82:83], v[18:19]
	v_pk_mul_f32 v[246:247], v[84:85], v[20:21]
	v_cvt_pk_bf16_f32 v192, v240, v241
	v_cvt_pk_bf16_f32 v193, v242, v243
	v_cvt_pk_bf16_f32 v194, v244, v245
	v_cvt_pk_bf16_f32 v195, v246, v247
	global_store_dwordx4 v202, v[192:195], s[46:47] offset:256
	v_fmac_f32_e32 v196, v22, v22
	v_fmac_f32_e32 v196, v23, v23
	v_fmac_f32_e32 v196, v24, v24
	v_fmac_f32_e32 v196, v25, v25
	v_fmac_f32_e32 v196, v18, v18
	v_fmac_f32_e32 v196, v19, v19
	v_fmac_f32_e32 v196, v20, v20
	v_fmac_f32_e32 v196, v21, v21
	v_mov_b32_e32 v198, v196
	s_nop 1
	v_permlane16_swap_b32_e32 v196, v198
	v_add_f32_e32 v196, v196, v198
	v_mov_b32_e32 v198, v196
	s_nop 1
	v_permlane32_swap_b32_e32 v196, v198
	v_add_f32_e32 v196, v196, v198
	v_add_u32_e32 v200, 0x5000, v201
	s_mov_b64 exec, s[38:39]
	global_store_dword v200, v196, s[50:51]
	s_mov_b64 exec, -1
	s_waitcnt vmcnt(16)
	v_pk_add_f32 v[14:15], v[14:15], v[180:181]
	v_pk_add_f32 v[16:17], v[16:17], v[182:183]
	v_pk_add_f32 v[10:11], v[10:11], v[184:185]
	v_pk_add_f32 v[12:13], v[12:13], v[186:187]
	global_store_dwordx4 v157, v[14:17], s[98:99] nt
	global_store_dwordx4 v157, v[10:13], s[98:99] offset:16 nt
	v_pk_mul_f32 v[180:181], v[102:103], v[14:15]
	v_pk_mul_f32 v[182:183], v[104:105], v[16:17]
	v_pk_mul_f32 v[184:185], v[98:99], v[10:11]
	v_pk_mul_f32 v[186:187], v[100:101], v[12:13]
	v_cvt_pk_bf16_f32 v188, v180, v181
	v_cvt_pk_bf16_f32 v189, v182, v183
	v_cvt_pk_bf16_f32 v190, v184, v185
	v_cvt_pk_bf16_f32 v191, v186, v187
	v_lshrrev_b32_e32 v203, 1, v157
	global_store_dwordx4 v203, v[188:191], s[46:47]
	v_mul_f32_e32 v197, v14, v14
	v_fmac_f32_e32 v197, v15, v15
	v_fmac_f32_e32 v197, v16, v16
	v_fmac_f32_e32 v197, v17, v17
	v_fmac_f32_e32 v197, v10, v10
	v_fmac_f32_e32 v197, v11, v11
	v_fmac_f32_e32 v197, v12, v12
	v_fmac_f32_e32 v197, v13, v13
	s_waitcnt vmcnt(14)
	v_pk_add_f32 v[6:7], v[6:7], v[210:211]
	v_pk_add_f32 v[8:9], v[8:9], v[212:213]
	v_pk_add_f32 v[2:3], v[2:3], v[214:215]
	v_pk_add_f32 v[4:5], v[4:5], v[216:217]
	global_store_dwordx4 v157, v[6:9], s[98:99] offset:512 nt
	global_store_dwordx4 v157, v[2:5], s[98:99] offset:528 nt
	v_pk_mul_f32 v[210:211], v[86:87], v[6:7]
	v_pk_mul_f32 v[212:213], v[88:89], v[8:9]
	v_pk_mul_f32 v[214:215], v[82:83], v[2:3]
	v_pk_mul_f32 v[216:217], v[84:85], v[4:5]
	v_cvt_pk_bf16_f32 v192, v210, v211
	v_cvt_pk_bf16_f32 v193, v212, v213
	v_cvt_pk_bf16_f32 v194, v214, v215
	v_cvt_pk_bf16_f32 v195, v216, v217
	global_store_dwordx4 v203, v[192:195], s[46:47] offset:256
	v_fmac_f32_e32 v197, v6, v6
	v_fmac_f32_e32 v197, v7, v7
	v_fmac_f32_e32 v197, v8, v8
	v_fmac_f32_e32 v197, v9, v9
	v_fmac_f32_e32 v197, v2, v2
	v_fmac_f32_e32 v197, v3, v3
	v_fmac_f32_e32 v197, v4, v4
	v_fmac_f32_e32 v197, v5, v5
	v_mov_b32_e32 v198, v197
	s_nop 1
	v_permlane16_swap_b32_e32 v197, v198
	v_add_f32_e32 v197, v197, v198
	v_mov_b32_e32 v198, v197
	s_nop 1
	v_permlane32_swap_b32_e32 v197, v198
	v_add_f32_e32 v197, v197, v198
	v_add_u32_e32 v200, 0x5800, v201
	s_mov_b64 exec, s[38:39]
	global_store_dword v200, v197, s[50:51]
	s_mov_b64 exec, -1

.LBB0_731:
	v_readlane_b32 s18, v253, 4
	v_readlane_b32 s19, v253, 5
	s_load_dwordx2 s[22:23], s[18:19], 0x98
	v_lshl_add_u32 v170, s5, 8, v149
	s_load_dwordx2 s[18:19], s[18:19], s58 offset:0x0
	v_lshl_or_b32 v168, s4, 8, v177
	v_lshlrev_b32_e32 v199, 11, v170
	v_add_lshl_u32 v199, v199, v168, 2
	v_lshlrev_b32_e32 v200, 2, v168
	v_lshlrev_b32_e32 v201, 7, v170
	s_waitcnt lgkmcnt(0)
	s_add_u32 s48, s22, 0x9f00000
	s_addc_u32 s49, s23, 0
	s_add_u32 s46, s22, 0xdf00000
	s_addc_u32 s47, s23, 0
	s_add_u32 s18, s18, s57
	s_addc_u32 s19, s19, 0
	s_lshl_b32 s4, s4, 2
	s_ashr_i32 s5, s4, 31
	s_lshl_b64 s[4:5], s[4:5], 2
	s_add_u32 s4, s22, s4
	s_addc_u32 s5, s23, s5
	s_add_u32 s4, s4, s59
	s_addc_u32 s5, s5, 0
	s_add_u32 s22, s4, 0x1a700000
	s_addc_u32 s23, s5, 0
	global_load_dwordx4 v[54:57], v200, s[18:19]
	global_load_dwordx4 v[50:53], v200, s[18:19] offset:16
	global_load_dwordx4 v[46:49], v200, s[18:19] offset:512
	global_load_dwordx4 v[42:45], v200, s[18:19] offset:528
	s_andn2_b64 vcc, exec, s[6:7]
	s_cbranch_vccnz .Lres_h_nocopy
	v_mov_b32_e32 v154, v199
	global_load_dwordx4 v[210:213], v154, s[48:49] nt
	global_load_dwordx4 v[214:217], v154, s[48:49] offset:16 nt
	global_load_dwordx4 v[218:221], v154, s[48:49] offset:512 nt
	global_load_dwordx4 v[222:225], v154, s[48:49] offset:528 nt
	v_add_u32_e32 v155, 0x20000, v199
	global_load_dwordx4 v[226:229], v155, s[48:49] nt
	global_load_dwordx4 v[236:239], v155, s[48:49] offset:16 nt
	global_load_dwordx4 v[240:243], v155, s[48:49] offset:512 nt
	global_load_dwordx4 v[244:247], v155, s[48:49] offset:528 nt
	v_add_u32_e32 v156, 0x40000, v199
	global_load_dwordx4 v[180:183], v156, s[48:49] nt
	global_load_dwordx4 v[184:187], v156, s[48:49] offset:16 nt
	s_waitcnt vmcnt(8)
	v_pk_add_f32 v[142:143], v[142:143], v[210:211]
	v_pk_add_f32 v[144:145], v[144:145], v[212:213]
	v_pk_add_f32 v[138:139], v[138:139], v[214:215]
	v_pk_add_f32 v[140:141], v[140:141], v[216:217]
	global_store_dwordx4 v154, v[142:145], s[48:49] nt
	global_store_dwordx4 v154, v[138:141], s[48:49] offset:16 nt
	v_pk_mul_f32 v[210:211], v[54:55], v[142:143]
	v_pk_mul_f32 v[212:213], v[56:57], v[144:145]
	v_pk_mul_f32 v[214:215], v[50:51], v[138:139]
	v_pk_mul_f32 v[216:217], v[52:53], v[140:141]
	v_cvt_pk_bf16_f32 v188, v210, v211
	v_cvt_pk_bf16_f32 v189, v212, v213
	v_cvt_pk_bf16_f32 v190, v214, v215
	v_cvt_pk_bf16_f32 v191, v216, v217
	v_lshrrev_b32_e32 v202, 1, v154
	global_store_dwordx4 v202, v[188:191], s[46:47]
	v_mul_f32_e32 v196, v142, v142
	v_fmac_f32_e32 v196, v143, v143
	v_fmac_f32_e32 v196, v144, v144
	v_fmac_f32_e32 v196, v145, v145
	v_fmac_f32_e32 v196, v138, v138
	v_fmac_f32_e32 v196, v139, v139
	v_fmac_f32_e32 v196, v140, v140
	v_fmac_f32_e32 v196, v141, v141
	global_load_dwordx4 v[210:213], v156, s[48:49] offset:512 nt
	global_load_dwordx4 v[214:217], v156, s[48:49] offset:528 nt
	s_waitcnt vmcnt(11)
	v_pk_add_f32 v[134:135], v[134:135], v[218:219]
	v_pk_add_f32 v[136:137], v[136:137], v[220:221]
	v_pk_add_f32 v[130:131], v[130:131], v[222:223]
	v_pk_add_f32 v[132:133], v[132:133], v[224:225]
	global_store_dwordx4 v154, v[134:137], s[48:49] offset:512 nt
	global_store_dwordx4 v154, v[130:133], s[48:49] offset:528 nt
	v_pk_mul_f32 v[218:219], v[46:47], v[134:135]
	v_pk_mul_f32 v[220:221], v[48:49], v[136:137]
	v_pk_mul_f32 v[222:223], v[42:43], v[130:131]
	v_pk_mul_f32 v[224:225], v[44:45], v[132:133]
	v_cvt_pk_bf16_f32 v192, v218, v219
	v_cvt_pk_bf16_f32 v193, v220, v221
	v_cvt_pk_bf16_f32 v194, v222, v223
	v_cvt_pk_bf16_f32 v195, v224, v225
	global_store_dwordx4 v202, v[192:195], s[46:47] offset:256
	v_fmac_f32_e32 v196, v134, v134
	v_fmac_f32_e32 v196, v135, v135
	v_fmac_f32_e32 v196, v136, v136
	v_fmac_f32_e32 v196, v137, v137
	v_fmac_f32_e32 v196, v130, v130
	v_fmac_f32_e32 v196, v131, v131
	v_fmac_f32_e32 v196, v132, v132
	v_fmac_f32_e32 v196, v133, v133
	v_mov_b32_e32 v198, v196
	s_nop 1
	v_permlane16_swap_b32_e32 v196, v198
	v_add_f32_e32 v196, v196, v198
	v_mov_b32_e32 v198, v196
	s_nop 1
	v_permlane32_swap_b32_e32 v196, v198
	v_add_f32_e32 v196, v196, v198
	v_mov_b32_e32 v200, v201
	s_mov_b64 exec, s[38:39]
	global_store_dword v200, v196, s[22:23]
	s_mov_b64 exec, -1
	v_add_u32_e32 v157, 0x60000, v199
	global_load_dwordx4 v[218:221], v157, s[48:49] nt
	global_load_dwordx4 v[222:225], v157, s[48:49] offset:16 nt
	s_waitcnt vmcnt(15)
	v_pk_add_f32 v[126:127], v[126:127], v[226:227]
	v_pk_add_f32 v[128:129], v[128:129], v[228:229]
	v_pk_add_f32 v[122:123], v[122:123], v[236:237]
	v_pk_add_f32 v[124:125], v[124:125], v[238:239]
	global_store_dwordx4 v155, v[126:129], s[48:49] nt
	global_store_dwordx4 v155, v[122:125], s[48:49] offset:16 nt
	v_pk_mul_f32 v[226:227], v[54:55], v[126:127]
	v_pk_mul_f32 v[228:229], v[56:57], v[128:129]
	v_pk_mul_f32 v[236:237], v[50:51], v[122:123]
	v_pk_mul_f32 v[238:239], v[52:53], v[124:125]
	v_cvt_pk_bf16_f32 v188, v226, v227
	v_cvt_pk_bf16_f32 v189, v228, v229
	v_cvt_pk_bf16_f32 v190, v236, v237
	v_cvt_pk_bf16_f32 v191, v238, v239
	v_lshrrev_b32_e32 v203, 1, v155
	global_store_dwordx4 v203, v[188:191], s[46:47]
	v_mul_f32_e32 v197, v126, v126
	v_fmac_f32_e32 v197, v127, v127
	v_fmac_f32_e32 v197, v128, v128
	v_fmac_f32_e32 v197, v129, v129
	v_fmac_f32_e32 v197, v122, v122
	v_fmac_f32_e32 v197, v123, v123
	v_fmac_f32_e32 v197, v124, v124
	v_fmac_f32_e32 v197, v125, v125
	global_load_dwordx4 v[226:229], v157, s[48:49] offset:512 nt
	global_load_dwordx4 v[236:239], v157, s[48:49] offset:528 nt
	s_waitcnt vmcnt(18)
	v_pk_add_f32 v[118:119], v[118:119], v[240:241]
	v_pk_add_f32 v[120:121], v[120:121], v[242:243]
	v_pk_add_f32 v[114:115], v[114:115], v[244:245]
	v_pk_add_f32 v[116:117], v[116:117], v[246:247]
	global_store_dwordx4 v155, v[118:121], s[48:49] offset:512 nt
	global_store_dwordx4 v155, v[114:117], s[48:49] offset:528 nt
	v_pk_mul_f32 v[240:241], v[46:47], v[118:119]
	v_pk_mul_f32 v[242:243], v[48:49], v[120:121]
	v_pk_mul_f32 v[244:245], v[42:43], v[114:115]
	v_pk_mul_f32 v[246:247], v[44:45], v[116:117]
	v_cvt_pk_bf16_f32 v192, v240, v241
	v_cvt_pk_bf16_f32 v193, v242, v243
	v_cvt_pk_bf16_f32 v194, v244, v245
	v_cvt_pk_bf16_f32 v195, v246, v247
	global_store_dwordx4 v203, v[192:195], s[46:47] offset:256
	v_fmac_f32_e32 v197, v118, v118
	v_fmac_f32_e32 v197, v119, v119
	v_fmac_f32_e32 v197, v120, v120
	v_fmac_f32_e32 v197, v121, v121
	v_fmac_f32_e32 v197, v114, v114
	v_fmac_f32_e32 v197, v115, v115
	v_fmac_f32_e32 v197, v116, v116
	v_fmac_f32_e32 v197, v117, v117
	v_mov_b32_e32 v198, v197
	s_nop 1
	v_permlane16_swap_b32_e32 v197, v198
	v_add_f32_e32 v197, v197, v198
	v_mov_b32_e32 v198, v197
	s_nop 1
	v_permlane32_swap_b32_e32 v197, v198
	v_add_f32_e32 v197, v197, v198
	v_add_u32_e32 v200, 0x800, v201
	s_mov_b64 exec, s[38:39]
	global_store_dword v200, v197, s[22:23]
	s_mov_b64 exec, -1
	v_add_u32_e32 v154, 0x100000, v199
	global_load_dwordx4 v[240:243], v154, s[48:49] nt
	global_load_dwordx4 v[244:247], v154, s[48:49] offset:16 nt
	s_waitcnt vmcnt(22)
	v_pk_add_f32 v[110:111], v[110:111], v[180:181]
	v_pk_add_f32 v[112:113], v[112:113], v[182:183]
	v_pk_add_f32 v[106:107], v[106:107], v[184:185]
	v_pk_add_f32 v[108:109], v[108:109], v[186:187]
	global_store_dwordx4 v156, v[110:113], s[48:49] nt
	global_store_dwordx4 v156, v[106:109], s[48:49] offset:16 nt
	v_pk_mul_f32 v[180:181], v[54:55], v[110:111]
	v_pk_mul_f32 v[182:183], v[56:57], v[112:113]
	v_pk_mul_f32 v[184:185], v[50:51], v[106:107]
	v_pk_mul_f32 v[186:187], v[52:53], v[108:109]
	v_cvt_pk_bf16_f32 v188, v180, v181
	v_cvt_pk_bf16_f32 v189, v182, v183
	v_cvt_pk_bf16_f32 v190, v184, v185
	v_cvt_pk_bf16_f32 v191, v186, v187
	v_lshrrev_b32_e32 v202, 1, v156
	global_store_dwordx4 v202, v[188:191], s[46:47]
	v_mul_f32_e32 v196, v110, v110
	v_fmac_f32_e32 v196, v111, v111
	v_fmac_f32_e32 v196, v112, v112
	v_fmac_f32_e32 v196, v113, v113
	v_fmac_f32_e32 v196, v106, v106
	v_fmac_f32_e32 v196, v107, v107
	v_fmac_f32_e32 v196, v108, v108
	v_fmac_f32_e32 v196, v109, v109
	global_load_dwordx4 v[180:183], v154, s[48:49] offset:512 nt
	global_load_dwordx4 v[184:187], v154, s[48:49] offset:528 nt
	s_waitcnt vmcnt(22)
	v_pk_add_f32 v[102:103], v[102:103], v[210:211]
	v_pk_add_f32 v[104:105], v[104:105], v[212:213]
	v_pk_add_f32 v[98:99], v[98:99], v[214:215]
	v_pk_add_f32 v[100:101], v[100:101], v[216:217]
	global_store_dwordx4 v156, v[102:105], s[48:49] offset:512 nt
	global_store_dwordx4 v156, v[98:101], s[48:49] offset:528 nt
	v_pk_mul_f32 v[210:211], v[46:47], v[102:103]
	v_pk_mul_f32 v[212:213], v[48:49], v[104:105]
	v_pk_mul_f32 v[214:215], v[42:43], v[98:99]
	v_pk_mul_f32 v[216:217], v[44:45], v[100:101]
	v_cvt_pk_bf16_f32 v192, v210, v211
	v_cvt_pk_bf16_f32 v193, v212, v213
	v_cvt_pk_bf16_f32 v194, v214, v215
	v_cvt_pk_bf16_f32 v195, v216, v217
	global_store_dwordx4 v202, v[192:195], s[46:47] offset:256
	v_fmac_f32_e32 v196, v102, v102
	v_fmac_f32_e32 v196, v103, v103
	v_fmac_f32_e32 v196, v104, v104
	v_fmac_f32_e32 v196, v105, v105
	v_fmac_f32_e32 v196, v98, v98
	v_fmac_f32_e32 v196, v99, v99
	v_fmac_f32_e32 v196, v100, v100
	v_fmac_f32_e32 v196, v101, v101
	v_mov_b32_e32 v198, v196
	s_nop 1
	v_permlane16_swap_b32_e32 v196, v198
	v_add_f32_e32 v196, v196, v198
	v_mov_b32_e32 v198, v196
	s_nop 1
	v_permlane32_swap_b32_e32 v196, v198
	v_add_f32_e32 v196, v196, v198
	v_add_u32_e32 v200, 0x1000, v201
	s_mov_b64 exec, s[38:39]
	global_store_dword v200, v196, s[22:23]
	s_mov_b64 exec, -1
	v_add_u32_e32 v155, 0x120000, v199
	global_load_dwordx4 v[210:213], v155, s[48:49] nt
	global_load_dwordx4 v[214:217], v155, s[48:49] offset:16 nt
	s_waitcnt vmcnt(22)
	v_pk_add_f32 v[94:95], v[94:95], v[218:219]
	v_pk_add_f32 v[96:97], v[96:97], v[220:221]
	v_pk_add_f32 v[90:91], v[90:91], v[222:223]
	v_pk_add_f32 v[92:93], v[92:93], v[224:225]
	global_store_dwordx4 v157, v[94:97], s[48:49] nt
	global_store_dwordx4 v157, v[90:93], s[48:49] offset:16 nt
	v_pk_mul_f32 v[218:219], v[54:55], v[94:95]
	v_pk_mul_f32 v[220:221], v[56:57], v[96:97]
	v_pk_mul_f32 v[222:223], v[50:51], v[90:91]
	v_pk_mul_f32 v[224:225], v[52:53], v[92:93]
	v_cvt_pk_bf16_f32 v188, v218, v219
	v_cvt_pk_bf16_f32 v189, v220, v221
	v_cvt_pk_bf16_f32 v190, v222, v223
	v_cvt_pk_bf16_f32 v191, v224, v225
	v_lshrrev_b32_e32 v203, 1, v157
	global_store_dwordx4 v203, v[188:191], s[46:47]
	v_mul_f32_e32 v197, v94, v94
	v_fmac_f32_e32 v197, v95, v95
	v_fmac_f32_e32 v197, v96, v96
	v_fmac_f32_e32 v197, v97, v97
	v_fmac_f32_e32 v197, v90, v90
	v_fmac_f32_e32 v197, v91, v91
	v_fmac_f32_e32 v197, v92, v92
	v_fmac_f32_e32 v197, v93, v93
	global_load_dwordx4 v[218:221], v155, s[48:49] offset:512 nt
	global_load_dwordx4 v[222:225], v155, s[48:49] offset:528 nt
	s_waitcnt vmcnt(22)
	v_pk_add_f32 v[86:87], v[86:87], v[226:227]
	v_pk_add_f32 v[88:89], v[88:89], v[228:229]
	v_pk_add_f32 v[82:83], v[82:83], v[236:237]
	v_pk_add_f32 v[84:85], v[84:85], v[238:239]
	global_store_dwordx4 v157, v[86:89], s[48:49] offset:512 nt
	global_store_dwordx4 v157, v[82:85], s[48:49] offset:528 nt
	v_pk_mul_f32 v[226:227], v[46:47], v[86:87]
	v_pk_mul_f32 v[228:229], v[48:49], v[88:89]
	v_pk_mul_f32 v[236:237], v[42:43], v[82:83]
	v_pk_mul_f32 v[238:239], v[44:45], v[84:85]
	v_cvt_pk_bf16_f32 v192, v226, v227
	v_cvt_pk_bf16_f32 v193, v228, v229
	v_cvt_pk_bf16_f32 v194, v236, v237
	v_cvt_pk_bf16_f32 v195, v238, v239
	global_store_dwordx4 v203, v[192:195], s[46:47] offset:256
	v_fmac_f32_e32 v197, v86, v86
	v_fmac_f32_e32 v197, v87, v87
	v_fmac_f32_e32 v197, v88, v88
	v_fmac_f32_e32 v197, v89, v89
	v_fmac_f32_e32 v197, v82, v82
	v_fmac_f32_e32 v197, v83, v83
	v_fmac_f32_e32 v197, v84, v84
	v_fmac_f32_e32 v197, v85, v85
	v_mov_b32_e32 v198, v197
	s_nop 1
	v_permlane16_swap_b32_e32 v197, v198
	v_add_f32_e32 v197, v197, v198
	v_mov_b32_e32 v198, v197
	s_nop 1
	v_permlane32_swap_b32_e32 v197, v198
	v_add_f32_e32 v197, v197, v198
	v_add_u32_e32 v200, 0x1800, v201
	s_mov_b64 exec, s[38:39]
	global_store_dword v200, v197, s[22:23]
	s_mov_b64 exec, -1
	v_add_u32_e32 v156, 0x140000, v199
	global_load_dwordx4 v[226:229], v156, s[48:49] nt
	global_load_dwordx4 v[236:239], v156, s[48:49] offset:16 nt
	s_waitcnt vmcnt(22)
	v_pk_add_f32 v[78:79], v[78:79], v[240:241]
	v_pk_add_f32 v[80:81], v[80:81], v[242:243]
	v_pk_add_f32 v[74:75], v[74:75], v[244:245]
	v_pk_add_f32 v[76:77], v[76:77], v[246:247]
	global_store_dwordx4 v154, v[78:81], s[48:49] nt
	global_store_dwordx4 v154, v[74:77], s[48:49] offset:16 nt
	v_pk_mul_f32 v[240:241], v[54:55], v[78:79]
	v_pk_mul_f32 v[242:243], v[56:57], v[80:81]
	v_pk_mul_f32 v[244:245], v[50:51], v[74:75]
	v_pk_mul_f32 v[246:247], v[52:53], v[76:77]
	v_cvt_pk_bf16_f32 v188, v240, v241
	v_cvt_pk_bf16_f32 v189, v242, v243
	v_cvt_pk_bf16_f32 v190, v244, v245
	v_cvt_pk_bf16_f32 v191, v246, v247
	v_lshrrev_b32_e32 v202, 1, v154
	global_store_dwordx4 v202, v[188:191], s[46:47]
	v_mul_f32_e32 v196, v78, v78
	v_fmac_f32_e32 v196, v79, v79
	v_fmac_f32_e32 v196, v80, v80
	v_fmac_f32_e32 v196, v81, v81
	v_fmac_f32_e32 v196, v74, v74
	v_fmac_f32_e32 v196, v75, v75
	v_fmac_f32_e32 v196, v76, v76
	v_fmac_f32_e32 v196, v77, v77
	global_load_dwordx4 v[240:243], v156, s[48:49] offset:512 nt
	global_load_dwordx4 v[244:247], v156, s[48:49] offset:528 nt
	s_waitcnt vmcnt(22)
	v_pk_add_f32 v[70:71], v[70:71], v[180:181]
	v_pk_add_f32 v[72:73], v[72:73], v[182:183]
	v_pk_add_f32 v[66:67], v[66:67], v[184:185]
	v_pk_add_f32 v[68:69], v[68:69], v[186:187]
	global_store_dwordx4 v154, v[70:73], s[48:49] offset:512 nt
	global_store_dwordx4 v154, v[66:69], s[48:49] offset:528 nt
	v_pk_mul_f32 v[180:181], v[46:47], v[70:71]
	v_pk_mul_f32 v[182:183], v[48:49], v[72:73]
	v_pk_mul_f32 v[184:185], v[42:43], v[66:67]
	v_pk_mul_f32 v[186:187], v[44:45], v[68:69]
	v_cvt_pk_bf16_f32 v192, v180, v181
	v_cvt_pk_bf16_f32 v193, v182, v183
	v_cvt_pk_bf16_f32 v194, v184, v185
	v_cvt_pk_bf16_f32 v195, v186, v187
	global_store_dwordx4 v202, v[192:195], s[46:47] offset:256
	v_fmac_f32_e32 v196, v70, v70
	v_fmac_f32_e32 v196, v71, v71
	v_fmac_f32_e32 v196, v72, v72
	v_fmac_f32_e32 v196, v73, v73
	v_fmac_f32_e32 v196, v66, v66
	v_fmac_f32_e32 v196, v67, v67
	v_fmac_f32_e32 v196, v68, v68
	v_fmac_f32_e32 v196, v69, v69
	v_mov_b32_e32 v198, v196
	s_nop 1
	v_permlane16_swap_b32_e32 v196, v198
	v_add_f32_e32 v196, v196, v198
	v_mov_b32_e32 v198, v196
	s_nop 1
	v_permlane32_swap_b32_e32 v196, v198
	v_add_f32_e32 v196, v196, v198
	v_add_u32_e32 v200, 0x4000, v201
	s_mov_b64 exec, s[38:39]
	global_store_dword v200, v196, s[22:23]
	s_mov_b64 exec, -1
	v_add_u32_e32 v157, 0x160000, v199
	global_load_dwordx4 v[180:183], v157, s[48:49] nt
	global_load_dwordx4 v[184:187], v157, s[48:49] offset:16 nt
	s_waitcnt vmcnt(22)
	v_pk_add_f32 v[62:63], v[62:63], v[210:211]
	v_pk_add_f32 v[64:65], v[64:65], v[212:213]
	v_pk_add_f32 v[58:59], v[58:59], v[214:215]
	v_pk_add_f32 v[60:61], v[60:61], v[216:217]
	global_store_dwordx4 v155, v[62:65], s[48:49] nt
	global_store_dwordx4 v155, v[58:61], s[48:49] offset:16 nt
	v_pk_mul_f32 v[210:211], v[54:55], v[62:63]
	v_pk_mul_f32 v[212:213], v[56:57], v[64:65]
	v_pk_mul_f32 v[214:215], v[50:51], v[58:59]
	v_pk_mul_f32 v[216:217], v[52:53], v[60:61]
	v_cvt_pk_bf16_f32 v188, v210, v211
	v_cvt_pk_bf16_f32 v189, v212, v213
	v_cvt_pk_bf16_f32 v190, v214, v215
	v_cvt_pk_bf16_f32 v191, v216, v217
	v_lshrrev_b32_e32 v203, 1, v155
	global_store_dwordx4 v203, v[188:191], s[46:47]
	v_mul_f32_e32 v197, v62, v62
	v_fmac_f32_e32 v197, v63, v63
	v_fmac_f32_e32 v197, v64, v64
	v_fmac_f32_e32 v197, v65, v65
	v_fmac_f32_e32 v197, v58, v58
	v_fmac_f32_e32 v197, v59, v59
	v_fmac_f32_e32 v197, v60, v60
	v_fmac_f32_e32 v197, v61, v61
	global_load_dwordx4 v[210:213], v157, s[48:49] offset:512 nt
	global_load_dwordx4 v[214:217], v157, s[48:49] offset:528 nt
	s_waitcnt vmcnt(22)
	v_pk_add_f32 v[38:39], v[38:39], v[218:219]
	v_pk_add_f32 v[40:41], v[40:41], v[220:221]
	v_pk_add_f32 v[34:35], v[34:35], v[222:223]
	v_pk_add_f32 v[36:37], v[36:37], v[224:225]
	global_store_dwordx4 v155, v[38:41], s[48:49] offset:512 nt
	global_store_dwordx4 v155, v[34:37], s[48:49] offset:528 nt
	v_pk_mul_f32 v[218:219], v[46:47], v[38:39]
	v_pk_mul_f32 v[220:221], v[48:49], v[40:41]
	v_pk_mul_f32 v[222:223], v[42:43], v[34:35]
	v_pk_mul_f32 v[224:225], v[44:45], v[36:37]
	v_cvt_pk_bf16_f32 v192, v218, v219
	v_cvt_pk_bf16_f32 v193, v220, v221
	v_cvt_pk_bf16_f32 v194, v222, v223
	v_cvt_pk_bf16_f32 v195, v224, v225
	global_store_dwordx4 v203, v[192:195], s[46:47] offset:256
	v_fmac_f32_e32 v197, v38, v38
	v_fmac_f32_e32 v197, v39, v39
	v_fmac_f32_e32 v197, v40, v40
	v_fmac_f32_e32 v197, v41, v41
	v_fmac_f32_e32 v197, v34, v34
	v_fmac_f32_e32 v197, v35, v35
	v_fmac_f32_e32 v197, v36, v36
	v_fmac_f32_e32 v197, v37, v37
	v_mov_b32_e32 v198, v197
	s_nop 1
	v_permlane16_swap_b32_e32 v197, v198
	v_add_f32_e32 v197, v197, v198
	v_mov_b32_e32 v198, v197
	s_nop 1
	v_permlane32_swap_b32_e32 v197, v198
	v_add_f32_e32 v197, v197, v198
	v_add_u32_e32 v200, 0x4800, v201
	s_mov_b64 exec, s[38:39]
	global_store_dword v200, v197, s[22:23]
	s_mov_b64 exec, -1
	s_waitcnt vmcnt(20)
	v_pk_add_f32 v[30:31], v[30:31], v[226:227]
	v_pk_add_f32 v[32:33], v[32:33], v[228:229]
	v_pk_add_f32 v[26:27], v[26:27], v[236:237]
	v_pk_add_f32 v[28:29], v[28:29], v[238:239]
	global_store_dwordx4 v156, v[30:33], s[48:49] nt
	global_store_dwordx4 v156, v[26:29], s[48:49] offset:16 nt
	v_pk_mul_f32 v[226:227], v[54:55], v[30:31]
	v_pk_mul_f32 v[228:229], v[56:57], v[32:33]
	v_pk_mul_f32 v[236:237], v[50:51], v[26:27]
	v_pk_mul_f32 v[238:239], v[52:53], v[28:29]
	v_cvt_pk_bf16_f32 v188, v226, v227
	v_cvt_pk_bf16_f32 v189, v228, v229
	v_cvt_pk_bf16_f32 v190, v236, v237
	v_cvt_pk_bf16_f32 v191, v238, v239
	v_lshrrev_b32_e32 v202, 1, v156
	global_store_dwordx4 v202, v[188:191], s[46:47]
	v_mul_f32_e32 v196, v30, v30
	v_fmac_f32_e32 v196, v31, v31
	v_fmac_f32_e32 v196, v32, v32
	v_fmac_f32_e32 v196, v33, v33
	v_fmac_f32_e32 v196, v26, v26
	v_fmac_f32_e32 v196, v27, v27
	v_fmac_f32_e32 v196, v28, v28
	v_fmac_f32_e32 v196, v29, v29
	s_waitcnt vmcnt(18)
	v_pk_add_f32 v[22:23], v[22:23], v[240:241]
	v_pk_add_f32 v[24:25], v[24:25], v[242:243]
	v_pk_add_f32 v[18:19], v[18:19], v[244:245]
	v_pk_add_f32 v[20:21], v[20:21], v[246:247]
	global_store_dwordx4 v156, v[22:25], s[48:49] offset:512 nt
	global_store_dwordx4 v156, v[18:21], s[48:49] offset:528 nt
	v_pk_mul_f32 v[240:241], v[46:47], v[22:23]
	v_pk_mul_f32 v[242:243], v[48:49], v[24:25]
	v_pk_mul_f32 v[244:245], v[42:43], v[18:19]
	v_pk_mul_f32 v[246:247], v[44:45], v[20:21]
	v_cvt_pk_bf16_f32 v192, v240, v241
	v_cvt_pk_bf16_f32 v193, v242, v243
	v_cvt_pk_bf16_f32 v194, v244, v245
	v_cvt_pk_bf16_f32 v195, v246, v247
	global_store_dwordx4 v202, v[192:195], s[46:47] offset:256
	v_fmac_f32_e32 v196, v22, v22
	v_fmac_f32_e32 v196, v23, v23
	v_fmac_f32_e32 v196, v24, v24
	v_fmac_f32_e32 v196, v25, v25
	v_fmac_f32_e32 v196, v18, v18
	v_fmac_f32_e32 v196, v19, v19
	v_fmac_f32_e32 v196, v20, v20
	v_fmac_f32_e32 v196, v21, v21
	v_mov_b32_e32 v198, v196
	s_nop 1
	v_permlane16_swap_b32_e32 v196, v198
	v_add_f32_e32 v196, v196, v198
	v_mov_b32_e32 v198, v196
	s_nop 1
	v_permlane32_swap_b32_e32 v196, v198
	v_add_f32_e32 v196, v196, v198
	v_add_u32_e32 v200, 0x5000, v201
	s_mov_b64 exec, s[38:39]
	global_store_dword v200, v196, s[22:23]
	s_mov_b64 exec, -1
	s_waitcnt vmcnt(16)
	v_pk_add_f32 v[14:15], v[14:15], v[180:181]
	v_pk_add_f32 v[16:17], v[16:17], v[182:183]
	v_pk_add_f32 v[10:11], v[10:11], v[184:185]
	v_pk_add_f32 v[12:13], v[12:13], v[186:187]
	global_store_dwordx4 v157, v[14:17], s[48:49] nt
	global_store_dwordx4 v157, v[10:13], s[48:49] offset:16 nt
	v_pk_mul_f32 v[180:181], v[54:55], v[14:15]
	v_pk_mul_f32 v[182:183], v[56:57], v[16:17]
	v_pk_mul_f32 v[184:185], v[50:51], v[10:11]
	v_pk_mul_f32 v[186:187], v[52:53], v[12:13]
	v_cvt_pk_bf16_f32 v188, v180, v181
	v_cvt_pk_bf16_f32 v189, v182, v183
	v_cvt_pk_bf16_f32 v190, v184, v185
	v_cvt_pk_bf16_f32 v191, v186, v187
	v_lshrrev_b32_e32 v203, 1, v157
	global_store_dwordx4 v203, v[188:191], s[46:47]
	v_mul_f32_e32 v197, v14, v14
	v_fmac_f32_e32 v197, v15, v15
	v_fmac_f32_e32 v197, v16, v16
	v_fmac_f32_e32 v197, v17, v17
	v_fmac_f32_e32 v197, v10, v10
	v_fmac_f32_e32 v197, v11, v11
	v_fmac_f32_e32 v197, v12, v12
	v_fmac_f32_e32 v197, v13, v13
	s_waitcnt vmcnt(14)
	v_pk_add_f32 v[6:7], v[6:7], v[210:211]
	v_pk_add_f32 v[8:9], v[8:9], v[212:213]
	v_pk_add_f32 v[2:3], v[2:3], v[214:215]
	v_pk_add_f32 v[4:5], v[4:5], v[216:217]
	global_store_dwordx4 v157, v[6:9], s[48:49] offset:512 nt
	global_store_dwordx4 v157, v[2:5], s[48:49] offset:528 nt
	v_pk_mul_f32 v[210:211], v[46:47], v[6:7]
	v_pk_mul_f32 v[212:213], v[48:49], v[8:9]
	v_pk_mul_f32 v[214:215], v[42:43], v[2:3]
	v_pk_mul_f32 v[216:217], v[44:45], v[4:5]
	v_cvt_pk_bf16_f32 v192, v210, v211
	v_cvt_pk_bf16_f32 v193, v212, v213
	v_cvt_pk_bf16_f32 v194, v214, v215
	v_cvt_pk_bf16_f32 v195, v216, v217
	global_store_dwordx4 v203, v[192:195], s[46:47] offset:256
	v_fmac_f32_e32 v197, v6, v6
	v_fmac_f32_e32 v197, v7, v7
	v_fmac_f32_e32 v197, v8, v8
	v_fmac_f32_e32 v197, v9, v9
	v_fmac_f32_e32 v197, v2, v2
	v_fmac_f32_e32 v197, v3, v3
	v_fmac_f32_e32 v197, v4, v4
	v_fmac_f32_e32 v197, v5, v5
	v_mov_b32_e32 v198, v197
	s_nop 1
	v_permlane16_swap_b32_e32 v197, v198
	v_add_f32_e32 v197, v197, v198
	v_mov_b32_e32 v198, v197
	s_nop 1
	v_permlane32_swap_b32_e32 v197, v198
	v_add_f32_e32 v197, v197, v198
	v_add_u32_e32 v200, 0x5800, v201
	s_mov_b64 exec, s[38:39]
	global_store_dword v200, v197, s[22:23]
	s_mov_b64 exec, -1
	s_branch .Lres_h_tail
.Lres_h_nocopy:
	v_mov_b32_e32 v154, v199
	global_load_dwordx4 v[210:213], v154, s[48:49] nt
	global_load_dwordx4 v[214:217], v154, s[48:49] offset:16 nt
	global_load_dwordx4 v[218:221], v154, s[48:49] offset:512 nt
	global_load_dwordx4 v[222:225], v154, s[48:49] offset:528 nt
	v_add_u32_e32 v155, 0x20000, v199
	global_load_dwordx4 v[226:229], v155, s[48:49] nt
	global_load_dwordx4 v[236:239], v155, s[48:49] offset:16 nt
	global_load_dwordx4 v[240:243], v155, s[48:49] offset:512 nt
	global_load_dwordx4 v[244:247], v155, s[48:49] offset:528 nt
	v_add_u32_e32 v156, 0x40000, v199
	global_load_dwordx4 v[180:183], v156, s[48:49] nt
	global_load_dwordx4 v[184:187], v156, s[48:49] offset:16 nt
	s_waitcnt vmcnt(8)
	v_pk_add_f32 v[142:143], v[142:143], v[210:211]
	v_pk_add_f32 v[144:145], v[144:145], v[212:213]
	v_pk_add_f32 v[138:139], v[138:139], v[214:215]
	v_pk_add_f32 v[140:141], v[140:141], v[216:217]
	global_store_dwordx4 v154, v[142:145], s[48:49] nt
	global_store_dwordx4 v154, v[138:141], s[48:49] offset:16 nt
	global_load_dwordx4 v[210:213], v156, s[48:49] offset:512 nt
	global_load_dwordx4 v[214:217], v156, s[48:49] offset:528 nt
	s_waitcnt vmcnt(10)
	v_pk_add_f32 v[134:135], v[134:135], v[218:219]
	v_pk_add_f32 v[136:137], v[136:137], v[220:221]
	v_pk_add_f32 v[130:131], v[130:131], v[222:223]
	v_pk_add_f32 v[132:133], v[132:133], v[224:225]
	global_store_dwordx4 v154, v[134:137], s[48:49] offset:512 nt
	global_store_dwordx4 v154, v[130:133], s[48:49] offset:528 nt
	v_add_u32_e32 v157, 0x60000, v199
	global_load_dwordx4 v[218:221], v157, s[48:49] nt
	global_load_dwordx4 v[222:225], v157, s[48:49] offset:16 nt
	s_waitcnt vmcnt(12)
	v_pk_add_f32 v[126:127], v[126:127], v[226:227]
	v_pk_add_f32 v[128:129], v[128:129], v[228:229]
	v_pk_add_f32 v[122:123], v[122:123], v[236:237]
	v_pk_add_f32 v[124:125], v[124:125], v[238:239]
	global_store_dwordx4 v155, v[126:129], s[48:49] nt
	global_store_dwordx4 v155, v[122:125], s[48:49] offset:16 nt
	global_load_dwordx4 v[226:229], v157, s[48:49] offset:512 nt
	global_load_dwordx4 v[236:239], v157, s[48:49] offset:528 nt
	s_waitcnt vmcnt(14)
	v_pk_add_f32 v[118:119], v[118:119], v[240:241]
	v_pk_add_f32 v[120:121], v[120:121], v[242:243]
	v_pk_add_f32 v[114:115], v[114:115], v[244:245]
	v_pk_add_f32 v[116:117], v[116:117], v[246:247]
	global_store_dwordx4 v155, v[118:121], s[48:49] offset:512 nt
	global_store_dwordx4 v155, v[114:117], s[48:49] offset:528 nt
	v_add_u32_e32 v154, 0x100000, v199
	global_load_dwordx4 v[240:243], v154, s[48:49] nt
	global_load_dwordx4 v[244:247], v154, s[48:49] offset:16 nt
	s_waitcnt vmcnt(16)
	v_pk_add_f32 v[110:111], v[110:111], v[180:181]
	v_pk_add_f32 v[112:113], v[112:113], v[182:183]
	v_pk_add_f32 v[106:107], v[106:107], v[184:185]
	v_pk_add_f32 v[108:109], v[108:109], v[186:187]
	global_store_dwordx4 v156, v[110:113], s[48:49] nt
	global_store_dwordx4 v156, v[106:109], s[48:49] offset:16 nt
	global_load_dwordx4 v[180:183], v154, s[48:49] offset:512 nt
	global_load_dwordx4 v[184:187], v154, s[48:49] offset:528 nt
	s_waitcnt vmcnt(16)
	v_pk_add_f32 v[102:103], v[102:103], v[210:211]
	v_pk_add_f32 v[104:105], v[104:105], v[212:213]
	v_pk_add_f32 v[98:99], v[98:99], v[214:215]
	v_pk_add_f32 v[100:101], v[100:101], v[216:217]
	global_store_dwordx4 v156, v[102:105], s[48:49] offset:512 nt
	global_store_dwordx4 v156, v[98:101], s[48:49] offset:528 nt
	v_add_u32_e32 v155, 0x120000, v199
	global_load_dwordx4 v[210:213], v155, s[48:49] nt
	global_load_dwordx4 v[214:217], v155, s[48:49] offset:16 nt
	s_waitcnt vmcnt(16)
	v_pk_add_f32 v[94:95], v[94:95], v[218:219]
	v_pk_add_f32 v[96:97], v[96:97], v[220:221]
	v_pk_add_f32 v[90:91], v[90:91], v[222:223]
	v_pk_add_f32 v[92:93], v[92:93], v[224:225]
	global_store_dwordx4 v157, v[94:97], s[48:49] nt
	global_store_dwordx4 v157, v[90:93], s[48:49] offset:16 nt
	global_load_dwordx4 v[218:221], v155, s[48:49] offset:512 nt
	global_load_dwordx4 v[222:225], v155, s[48:49] offset:528 nt
	s_waitcnt vmcnt(16)
	v_pk_add_f32 v[86:87], v[86:87], v[226:227]
	v_pk_add_f32 v[88:89], v[88:89], v[228:229]
	v_pk_add_f32 v[82:83], v[82:83], v[236:237]
	v_pk_add_f32 v[84:85], v[84:85], v[238:239]
	global_store_dwordx4 v157, v[86:89], s[48:49] offset:512 nt
	global_store_dwordx4 v157, v[82:85], s[48:49] offset:528 nt
	v_add_u32_e32 v156, 0x140000, v199
	global_load_dwordx4 v[226:229], v156, s[48:49] nt
	global_load_dwordx4 v[236:239], v156, s[48:49] offset:16 nt
	s_waitcnt vmcnt(16)
	v_pk_add_f32 v[78:79], v[78:79], v[240:241]
	v_pk_add_f32 v[80:81], v[80:81], v[242:243]
	v_pk_add_f32 v[74:75], v[74:75], v[244:245]
	v_pk_add_f32 v[76:77], v[76:77], v[246:247]
	global_store_dwordx4 v154, v[78:81], s[48:49] nt
	global_store_dwordx4 v154, v[74:77], s[48:49] offset:16 nt
	global_load_dwordx4 v[240:243], v156, s[48:49] offset:512 nt
	global_load_dwordx4 v[244:247], v156, s[48:49] offset:528 nt
	s_waitcnt vmcnt(16)
	v_pk_add_f32 v[70:71], v[70:71], v[180:181]
	v_pk_add_f32 v[72:73], v[72:73], v[182:183]
	v_pk_add_f32 v[66:67], v[66:67], v[184:185]
	v_pk_add_f32 v[68:69], v[68:69], v[186:187]
	global_store_dwordx4 v154, v[70:73], s[48:49] offset:512 nt
	global_store_dwordx4 v154, v[66:69], s[48:49] offset:528 nt
	v_add_u32_e32 v157, 0x160000, v199
	global_load_dwordx4 v[180:183], v157, s[48:49] nt
	global_load_dwordx4 v[184:187], v157, s[48:49] offset:16 nt
	s_waitcnt vmcnt(16)
	v_pk_add_f32 v[62:63], v[62:63], v[210:211]
	v_pk_add_f32 v[64:65], v[64:65], v[212:213]
	v_pk_add_f32 v[58:59], v[58:59], v[214:215]
	v_pk_add_f32 v[60:61], v[60:61], v[216:217]
	global_store_dwordx4 v155, v[62:65], s[48:49] nt
	global_store_dwordx4 v155, v[58:61], s[48:49] offset:16 nt
	global_load_dwordx4 v[210:213], v157, s[48:49] offset:512 nt
	global_load_dwordx4 v[214:217], v157, s[48:49] offset:528 nt
	s_waitcnt vmcnt(16)
	v_pk_add_f32 v[38:39], v[38:39], v[218:219]
	v_pk_add_f32 v[40:41], v[40:41], v[220:221]
	v_pk_add_f32 v[34:35], v[34:35], v[222:223]
	v_pk_add_f32 v[36:37], v[36:37], v[224:225]
	global_store_dwordx4 v155, v[38:41], s[48:49] offset:512 nt
	global_store_dwordx4 v155, v[34:37], s[48:49] offset:528 nt
	s_waitcnt vmcnt(14)
	v_pk_add_f32 v[30:31], v[30:31], v[226:227]
	v_pk_add_f32 v[32:33], v[32:33], v[228:229]
	v_pk_add_f32 v[26:27], v[26:27], v[236:237]
	v_pk_add_f32 v[28:29], v[28:29], v[238:239]
	global_store_dwordx4 v156, v[30:33], s[48:49] nt
	global_store_dwordx4 v156, v[26:29], s[48:49] offset:16 nt
	s_waitcnt vmcnt(12)
	v_pk_add_f32 v[22:23], v[22:23], v[240:241]
	v_pk_add_f32 v[24:25], v[24:25], v[242:243]
	v_pk_add_f32 v[18:19], v[18:19], v[244:245]
	v_pk_add_f32 v[20:21], v[20:21], v[246:247]
	global_store_dwordx4 v156, v[22:25], s[48:49] offset:512 nt
	global_store_dwordx4 v156, v[18:21], s[48:49] offset:528 nt
	s_waitcnt vmcnt(10)
	v_pk_add_f32 v[14:15], v[14:15], v[180:181]
	v_pk_add_f32 v[16:17], v[16:17], v[182:183]
	v_pk_add_f32 v[10:11], v[10:11], v[184:185]
	v_pk_add_f32 v[12:13], v[12:13], v[186:187]
	global_store_dwordx4 v157, v[14:17], s[48:49] nt
	global_store_dwordx4 v157, v[10:13], s[48:49] offset:16 nt
	s_waitcnt vmcnt(8)
	v_pk_add_f32 v[6:7], v[6:7], v[210:211]
	v_pk_add_f32 v[8:9], v[8:9], v[212:213]
	v_pk_add_f32 v[2:3], v[2:3], v[214:215]
	v_pk_add_f32 v[4:5], v[4:5], v[216:217]
	global_store_dwordx4 v157, v[6:9], s[48:49] offset:512 nt
	global_store_dwordx4 v157, v[2:5], s[48:49] offset:528 nt
